# P0 rows loop: loop-carried vmcnt(8) dropped so the second round's 12 remaining loads do not wait for the first round's stores
# baseline (speedup 1.0000x reference)
.LBB0_44:
	global_load_dwordx4 v[76:79], v[88:89], off offset:-2048 nt
	global_load_dwordx4 v[72:75], v[88:89], off offset:-1024 nt
	global_load_dwordx4 v[68:71], v[88:89], off nt
	global_load_dwordx4 v[64:67], v[88:89], off offset:1024 nt
	s_add_i32 s22, s34, s6
	s_cmpk_lt_i32 s22, 0x4000
	s_cselect_b64 s[30:31], -1, 0
	s_and_b64 s[4:5], s[30:31], exec
	s_cselect_b32 s4, s22, s6
	s_ashr_i32 s5, s4, 31
	s_add_i32 s26, s35, s6
	s_lshl_b64 s[4:5], s[4:5], 12
	s_cmpk_lt_i32 s26, 0x4000
	s_cselect_b64 s[28:29], -1, 0
	v_lshl_add_u64 v[16:17], v[80:81], 0, s[4:5]
	s_and_b64 s[4:5], s[28:29], exec
	s_cselect_b32 s4, s26, s6
	s_ashr_i32 s5, s4, 31
	s_add_i32 s22, s36, s6
	s_lshl_b64 s[4:5], s[4:5], 12
	s_cmpk_lt_i32 s22, 0x4000
	s_cselect_b64 s[24:25], -1, 0
	global_load_dwordx4 v[60:63], v[16:17], off nt
	global_load_dwordx4 v[56:59], v[16:17], off offset:1024 nt
	global_load_dwordx4 v[52:55], v[16:17], off offset:2048 nt
	global_load_dwordx4 v[48:51], v[16:17], off offset:3072 nt
	v_lshl_add_u64 v[16:17], v[80:81], 0, s[4:5]
	s_and_b64 s[4:5], s[24:25], exec
	s_cselect_b32 s4, s22, s6
	s_ashr_i32 s5, s4, 31
	s_lshl_b64 s[4:5], s[4:5], 12
	global_load_dwordx4 v[44:47], v[16:17], off nt
	global_load_dwordx4 v[40:43], v[16:17], off offset:1024 nt
	global_load_dwordx4 v[36:39], v[16:17], off offset:2048 nt
	global_load_dwordx4 v[32:35], v[16:17], off offset:3072 nt
	v_lshl_add_u64 v[16:17], v[80:81], 0, s[4:5]
	global_load_dwordx4 v[28:31], v[16:17], off nt
	global_load_dwordx4 v[24:27], v[16:17], off offset:1024 nt
	global_load_dwordx4 v[20:23], v[16:17], off offset:2048 nt
	s_nop 0
	global_load_dwordx4 v[16:19], v[16:17], off offset:3072 nt
	s_waitcnt vmcnt(15)
	v_mul_f32_e32 v98, v77, v77
	v_mul_f32_e32 v99, v79, v79
	s_waitcnt vmcnt(14)
	v_mul_f32_e32 v100, v73, v73
	v_mul_f32_e32 v101, v75, v75
	s_waitcnt vmcnt(13)
	v_mul_f32_e32 v102, v69, v69
	v_mul_f32_e32 v103, v71, v71
	v_fmac_f32_e32 v98, v76, v76
	v_fmac_f32_e32 v99, v78, v78
	v_fmac_f32_e32 v100, v72, v72
	v_fmac_f32_e32 v101, v74, v74
	s_waitcnt vmcnt(12)
	v_mul_f32_e32 v104, v65, v65
	v_mul_f32_e32 v105, v67, v67
	v_fmac_f32_e32 v102, v68, v68
	v_fmac_f32_e32 v103, v70, v70
	v_add_f32_e32 v98, v98, v99
	v_add_f32_e32 v99, v100, v101
	v_fmac_f32_e32 v104, v64, v64
	v_fmac_f32_e32 v105, v66, v66
	v_add_f32_e32 v100, v102, v103
	v_add_f32_e32 v98, v99, v98
	v_add_f32_e32 v101, v104, v105
	v_add_f32_e32 v98, v100, v98
	v_add_f32_e32 v98, v101, v98
	ds_bpermute_b32 v99, v90, v98
	s_waitcnt lgkmcnt(0)
	v_add_f32_e32 v98, v98, v99
	ds_bpermute_b32 v99, v91, v98
	s_waitcnt lgkmcnt(0)
	v_add_f32_e32 v98, v98, v99
	ds_bpermute_b32 v99, v92, v98
	s_waitcnt lgkmcnt(0)
	v_add_f32_e32 v98, v98, v99
	ds_bpermute_b32 v99, v93, v98
	s_waitcnt lgkmcnt(0)
	v_add_f32_e32 v98, v98, v99
	ds_bpermute_b32 v99, v94, v98
	s_waitcnt lgkmcnt(0)
	v_add_f32_e32 v98, v98, v99
	ds_bpermute_b32 v99, v95, v98
	s_waitcnt lgkmcnt(0)
	v_add_f32_e32 v98, v98, v99
	v_fmamk_f32 v98, v98, 0x3a800000, v96
	v_mul_f32_e32 v99, 0x4f800000, v98
	v_cmp_gt_f32_e32 vcc, s7, v98
	s_nop 1
	v_cndmask_b32_e32 v98, v98, v99, vcc
	v_sqrt_f32_e32 v99, v98
	s_nop 0
	v_add_u32_e32 v100, -1, v99
	v_add_u32_e32 v101, 1, v99
	v_fma_f32 v102, -v100, v99, v98
	v_fma_f32 v103, -v101, v99, v98
	v_cmp_ge_f32_e64 s[4:5], 0, v102
	s_nop 1
	v_cndmask_b32_e64 v99, v99, v100, s[4:5]
	v_cmp_lt_f32_e64 s[4:5], 0, v103
	s_nop 1
	v_cndmask_b32_e64 v99, v99, v101, s[4:5]
	v_mul_f32_e32 v100, 0x37800000, v99
	v_cndmask_b32_e32 v99, v99, v100, vcc
	v_cmp_class_f32_e32 vcc, v98, v97
	s_nop 1
	v_cndmask_b32_e32 v98, v99, v98, vcc
	s_and_saveexec_b64 s[4:5], s[0:1]
	s_cbranch_execz .LBB0_46
	s_add_u32 s44, s66, s39
	s_addc_u32 s45, s67, s40
	global_store_dword v247, v98, s[44:45]
